# GEMM K-loops: single-use 64-bit address adds folded into saddr-form global_load_lds (12 VALU ops removed from the load segments)
# baseline (speedup 1.0000x reference)
; #define PG8_STAGE(bufoff, gbase, voff) do { _Pragma("unroll") for (int _i = 0; _i < 2; ++_i) \
;         __builtin_amdgcn_global_load_lds((const unsigned*)((const char*)(gbase) + (voff)[_i]), (PG8_LAS unsigned*)(lds + (bufoff) + ldsw + _i * 8192), 16, 0, 0); } while (0)
; #define PG8_LDA(dst, b, h) do { _Pragma("unroll") for (int m = 0; m < 4; ++m) _Pragma("unroll") for (int k = 0; k < 2; ++k) dst[m][k] = *(const PG8_LAS bf16x8*)(lds + PG8_SA(b, h) + aoff + m * 2048 + k * 1024); } while (0)
; #define PG8_LDB(dst, b, h) do { _Pragma("unroll") for (int n = 0; n < 2; ++n) _Pragma("unroll") for (int k = 0; k < 2; ++k) dst[n][k] = *(const PG8_LAS bf16x8*)(lds + PG8_SB(b, h) + boff + n * 2048 + k * 1024); } while (0)
; #define PG8_MMA(ai, bj, At, Bt) do { __builtin_amdgcn_s_setprio(1); _Pragma("unroll") for (int m = 0; m < 4; ++m) _Pragma("unroll") for (int n = 0; n < 2; ++n) _Pragma("unroll") for (int k = 0; k < 2; ++k) \
;         acc[ai][bj][m][n] = __builtin_amdgcn_mfma_f32_16x16x32_bf16(Bt[n][k], At[m][k], acc[ai][bj][m][n], 0, 0, 0); __builtin_amdgcn_s_setprio(0); } while (0)
; #define PG8_WAIT_V(n) asm volatile("s_waitcnt vmcnt(" #n ")" ::: "memory")
; #define PG8_WAIT_L(n) asm volatile("s_waitcnt lgkmcnt(" #n ")" ::: "memory")
; #define PG8_BAR __builtin_amdgcn_s_barrier()
; #define PG8_SCHED __builtin_amdgcn_sched_barrier(0)
; template <class Epi, class Sched, bool ALIGN_EPI = false, bool SP2 = false>
; __device__ __forceinline__ void gemm_phase(PG8_LAS unsigned char* lds, const Gemm g, const Sched& S, const Epi& E) {
;     ...
;             PG8_LDB(B0, 0, 0); PG8_LDB(B1, 0, 1); PG8_SCHED; PG8_LDA(At, 0, 0); PG8_STAGE(PG8_SA(1, 1), a1 + hstep, voffA);
;             PG8_WAIT_V(8); PG8_WAIT_L(0); PG8_BAR; PG8_MMA(0, 0, At, B0); PG8_MMA(0, 1, At, B1); PG8_BAR; PG8_SCHED;
;             PG8_LDA(At, 0, 1); PG8_STAGE(PG8_SB(0, 0), b2, voffB); PG8_STAGE(PG8_SB(0, 1), b2 + hstep, voffB); PG8_STAGE(PG8_SA(0, 0), a2, voffA);
;             PG8_WAIT_V(8); PG8_WAIT_L(0); PG8_BAR; PG8_MMA(1, 0, At, B0); PG8_MMA(1, 1, At, B1); PG8_BAR; PG8_SCHED;
.LBB0_100:
	s_add_u32 s16, s24, 0xfff80080
	s_addc_u32 s17, s25, -1
	s_add_i32 s45, 0, 0x10000
	s_cmp_eq_u32 s44, 28
	s_cselect_b32 s19, s11, s17
	s_cselect_b32 s18, s38, s16
	s_cselect_b32 s17, s9, s41
	s_cselect_b32 s16, s39, s40
	s_add_i32 s48, 0, 0x14000
	v_add_u32_e32 v156, s45, v145
	v_add_u32_e32 v172, s48, v145
	ds_read_b128 v[140:143], v156
	ds_read_b128 v[148:151], v156 offset:1024
	ds_read_b128 v[152:155], v156 offset:2048
	ds_read_b128 v[156:159], v156 offset:3072
	ds_read_b128 v[160:163], v172
	ds_read_b128 v[164:167], v172 offset:1024
	ds_read_b128 v[168:171], v172 offset:2048
	ds_read_b128 v[172:175], v172 offset:3072
	s_add_i32 m0, s1, 0xc000
	ds_read_b128 v[180:183], v147
	ds_read_b128 v[184:187], v147 offset:1024
	ds_read_b128 v[202:205], v147 offset:2048
	ds_read_b128 v[206:209], v147 offset:3072
	ds_read_b128 v[210:213], v147 offset:4096
	ds_read_b128 v[214:217], v147 offset:5120
	ds_read_b128 v[218:221], v147 offset:6144
	ds_read_b128 v[222:225], v147 offset:7168
	global_load_lds_dwordx4 v136, s[24:25]
	s_add_i32 m0, s1, 0xe000
	s_nop 0
	global_load_lds_dwordx4 v138, s[24:25]
	s_waitcnt vmcnt(8)
	s_waitcnt lgkmcnt(0)
	s_barrier
	s_setprio 1
	s_waitcnt lgkmcnt(0)
	v_mfma_f32_16x16x32_bf16 v[126:129], v[140:143], v[180:183], v[126:129]
	v_mfma_f32_16x16x32_bf16 v[122:125], v[152:155], v[180:183], v[122:125]
	v_mfma_f32_16x16x32_bf16 v[110:113], v[140:143], v[202:205], v[110:113]
	v_mfma_f32_16x16x32_bf16 v[106:109], v[152:155], v[202:205], v[106:109]
	v_mfma_f32_16x16x32_bf16 v[94:97], v[140:143], v[210:213], v[94:97]
	v_mfma_f32_16x16x32_bf16 v[90:93], v[152:155], v[210:213], v[90:93]
	v_mfma_f32_16x16x32_bf16 v[78:81], v[140:143], v[218:221], v[78:81]
	v_mfma_f32_16x16x32_bf16 v[74:77], v[152:155], v[218:221], v[74:77]
	v_mfma_f32_16x16x32_bf16 v[126:129], v[148:151], v[184:187], v[126:129]
	v_mfma_f32_16x16x32_bf16 v[122:125], v[156:159], v[184:187], v[122:125]
	v_mfma_f32_16x16x32_bf16 v[110:113], v[148:151], v[206:209], v[110:113]
	v_mfma_f32_16x16x32_bf16 v[106:109], v[156:159], v[206:209], v[106:109]
	v_mfma_f32_16x16x32_bf16 v[94:97], v[148:151], v[214:217], v[94:97]
	v_mfma_f32_16x16x32_bf16 v[90:93], v[156:159], v[214:217], v[90:93]
	v_mfma_f32_16x16x32_bf16 v[78:81], v[148:151], v[222:225], v[78:81]
	v_mfma_f32_16x16x32_bf16 v[74:77], v[156:159], v[222:225], v[74:77]
	s_setprio 0
	s_setprio 1
	v_mfma_f32_16x16x32_bf16 v[118:121], v[160:163], v[180:183], v[118:121]
	v_mfma_f32_16x16x32_bf16 v[114:117], v[168:171], v[180:183], v[114:117]
	v_mfma_f32_16x16x32_bf16 v[102:105], v[160:163], v[202:205], v[102:105]
	v_mfma_f32_16x16x32_bf16 v[98:101], v[168:171], v[202:205], v[98:101]
	v_mfma_f32_16x16x32_bf16 v[86:89], v[160:163], v[210:213], v[86:89]
	v_mfma_f32_16x16x32_bf16 v[82:85], v[168:171], v[210:213], v[82:85]
	v_mfma_f32_16x16x32_bf16 v[70:73], v[160:163], v[218:221], v[70:73]
	v_mfma_f32_16x16x32_bf16 v[66:69], v[168:171], v[218:221], v[66:69]
	v_mfma_f32_16x16x32_bf16 v[118:121], v[164:167], v[184:187], v[118:121]
	v_mfma_f32_16x16x32_bf16 v[114:117], v[172:175], v[184:187], v[114:117]
	v_mfma_f32_16x16x32_bf16 v[102:105], v[164:167], v[206:209], v[102:105]
	v_mfma_f32_16x16x32_bf16 v[98:101], v[172:175], v[206:209], v[98:101]
	v_mfma_f32_16x16x32_bf16 v[86:89], v[164:167], v[214:217], v[86:89]
	v_mfma_f32_16x16x32_bf16 v[82:85], v[172:175], v[214:217], v[82:85]
	v_mfma_f32_16x16x32_bf16 v[70:73], v[164:167], v[222:225], v[70:73]
	v_mfma_f32_16x16x32_bf16 v[66:69], v[172:175], v[222:225], v[66:69]
	s_setprio 0
	s_barrier
	s_add_i32 s45, s45, s0
	v_lshl_add_u64 v[176:177], s[16:17], 0, v[0:1]
	s_mov_b32 m0, s45
	ds_read_b128 v[180:183], v147 offset:16384
	ds_read_b128 v[184:187], v147 offset:17408
	ds_read_b128 v[202:205], v147 offset:18432
	ds_read_b128 v[206:209], v147 offset:19456
	ds_read_b128 v[210:213], v147 offset:20480
	ds_read_b128 v[214:217], v147 offset:21504
	ds_read_b128 v[218:221], v147 offset:22528
	ds_read_b128 v[222:225], v147 offset:23552
	global_load_lds_dwordx4 v[176:177], off
	s_add_i32 m0, s45, 0x2000
	s_add_u32 s46, s16, 0x80000
	v_lshl_add_u64 v[188:189], s[16:17], 0, v[130:131]
	s_addc_u32 s47, s17, 0
	s_add_i32 s45, s48, s0
	global_load_lds_dwordx4 v[188:189], off
	s_mov_b32 m0, s45
	v_lshl_add_u64 v[228:229], s[18:19], 0, v[132:133]
	global_load_lds_dwordx4 v0, s[46:47]
	s_add_i32 m0, s45, 0x2000
	s_nop 0
	global_load_lds_dwordx4 v130, s[46:47]
	v_lshl_add_u64 v[226:227], s[18:19], 0, v[134:135]
	s_mov_b32 m0, s1
	s_nop 0
	global_load_lds_dwordx4 v[226:227], off
	s_mov_b32 m0, s14
	s_nop 0
	global_load_lds_dwordx4 v[228:229], off
	s_waitcnt vmcnt(8)
	s_waitcnt lgkmcnt(0)
	s_barrier
; #define PG8_STAGE(bufoff, gbase, voff) do { _Pragma("unroll") for (int _i = 0; _i < 2; ++_i) \
;         __builtin_amdgcn_global_load_lds((const unsigned*)((const char*)(gbase) + (voff)[_i]), (PG8_LAS unsigned*)(lds + (bufoff) + ldsw + _i * 8192), 16, 0, 0); } while (0)
; #define PG8_LDA(dst, b, h) do { _Pragma("unroll") for (int m = 0; m < 4; ++m) _Pragma("unroll") for (int k = 0; k < 2; ++k) dst[m][k] = *(const PG8_LAS bf16x8*)(lds + PG8_SA(b, h) + aoff + m * 2048 + k * 1024); } while (0)
; #define PG8_LDB(dst, b, h) do { _Pragma("unroll") for (int n = 0; n < 2; ++n) _Pragma("unroll") for (int k = 0; k < 2; ++k) dst[n][k] = *(const PG8_LAS bf16x8*)(lds + PG8_SB(b, h) + boff + n * 2048 + k * 1024); } while (0)
; #define PG8_MMA(ai, bj, At, Bt) do { __builtin_amdgcn_s_setprio(1); _Pragma("unroll") for (int m = 0; m < 4; ++m) _Pragma("unroll") for (int n = 0; n < 2; ++n) _Pragma("unroll") for (int k = 0; k < 2; ++k) \
;         acc[ai][bj][m][n] = __builtin_amdgcn_mfma_f32_16x16x32_bf16(Bt[n][k], At[m][k], acc[ai][bj][m][n], 0, 0, 0); __builtin_amdgcn_s_setprio(0); } while (0)
; #define PG8_WAIT_V(n) asm volatile("s_waitcnt vmcnt(" #n ")" ::: "memory")
; #define PG8_WAIT_L(n) asm volatile("s_waitcnt lgkmcnt(" #n ")" ::: "memory")
; #define PG8_BAR __builtin_amdgcn_s_barrier()
; #define PG8_SCHED __builtin_amdgcn_sched_barrier(0)
; template <class Epi, class Sched, bool ALIGN_EPI = false, bool SP2 = false>
; __device__ __forceinline__ void gemm_phase(PG8_LAS unsigned char* lds, const Gemm g, const Sched& S, const Epi& E) {
;     ...
;             PG8_WAIT_V(8); PG8_WAIT_L(0); PG8_BAR; PG8_MMA(1, 0, At, B0); PG8_MMA(1, 1, At, B1); PG8_BAR; PG8_SCHED;
;             PG8_LDB(B0, 1, 0); PG8_LDB(B1, 1, 1); PG8_SCHED; PG8_LDA(At, 1, 0); PG8_STAGE(PG8_SA(0, 1), a2 + hstep, voffA);
;             PG8_WAIT_V(8); PG8_WAIT_L(0); PG8_BAR; PG8_MMA(0, 0, At, B0); PG8_MMA(0, 1, At, B1); PG8_BAR; PG8_SCHED;
;             PG8_LDA(At, 1, 1); PG8_STAGE(PG8_SB(1, 0), b3, voffB); PG8_STAGE(PG8_SB(1, 1), b3 + hstep, voffB); PG8_STAGE(PG8_SA(1, 0), a3, voffA);
	s_setprio 1
	s_waitcnt lgkmcnt(0)
	v_mfma_f32_16x16x32_bf16 v[62:65], v[140:143], v[180:183], v[62:65]
	v_mfma_f32_16x16x32_bf16 v[58:61], v[152:155], v[180:183], v[58:61]
	v_mfma_f32_16x16x32_bf16 v[46:49], v[140:143], v[202:205], v[46:49]
	v_mfma_f32_16x16x32_bf16 v[42:45], v[152:155], v[202:205], v[42:45]
	v_mfma_f32_16x16x32_bf16 v[30:33], v[140:143], v[210:213], v[30:33]
	v_mfma_f32_16x16x32_bf16 v[26:29], v[152:155], v[210:213], v[26:29]
	v_mfma_f32_16x16x32_bf16 v[14:17], v[140:143], v[218:221], v[14:17]
	v_mfma_f32_16x16x32_bf16 v[10:13], v[152:155], v[218:221], v[10:13]
	v_mfma_f32_16x16x32_bf16 v[62:65], v[148:151], v[184:187], v[62:65]
	v_mfma_f32_16x16x32_bf16 v[58:61], v[156:159], v[184:187], v[58:61]
	v_mfma_f32_16x16x32_bf16 v[46:49], v[148:151], v[206:209], v[46:49]
	v_mfma_f32_16x16x32_bf16 v[42:45], v[156:159], v[206:209], v[42:45]
	v_mfma_f32_16x16x32_bf16 v[30:33], v[148:151], v[214:217], v[30:33]
	v_mfma_f32_16x16x32_bf16 v[26:29], v[156:159], v[214:217], v[26:29]
	v_mfma_f32_16x16x32_bf16 v[14:17], v[148:151], v[222:225], v[14:17]
	v_mfma_f32_16x16x32_bf16 v[10:13], v[156:159], v[222:225], v[10:13]
	s_setprio 0
	s_setprio 1
	v_mfma_f32_16x16x32_bf16 v[54:57], v[160:163], v[180:183], v[54:57]
	v_mfma_f32_16x16x32_bf16 v[50:53], v[168:171], v[180:183], v[50:53]
	v_mfma_f32_16x16x32_bf16 v[38:41], v[160:163], v[202:205], v[38:41]
	v_mfma_f32_16x16x32_bf16 v[34:37], v[168:171], v[202:205], v[34:37]
	v_mfma_f32_16x16x32_bf16 v[22:25], v[160:163], v[210:213], v[22:25]
	v_mfma_f32_16x16x32_bf16 v[18:21], v[168:171], v[210:213], v[18:21]
	v_mfma_f32_16x16x32_bf16 v[6:9], v[160:163], v[218:221], v[6:9]
	v_mfma_f32_16x16x32_bf16 v[2:5], v[168:171], v[218:221], v[2:5]
	v_mfma_f32_16x16x32_bf16 v[54:57], v[164:167], v[184:187], v[54:57]
	v_mfma_f32_16x16x32_bf16 v[50:53], v[172:175], v[184:187], v[50:53]
	v_mfma_f32_16x16x32_bf16 v[38:41], v[164:167], v[206:209], v[38:41]
	v_mfma_f32_16x16x32_bf16 v[34:37], v[172:175], v[206:209], v[34:37]
	v_mfma_f32_16x16x32_bf16 v[22:25], v[164:167], v[214:217], v[22:25]
	v_mfma_f32_16x16x32_bf16 v[18:21], v[172:175], v[214:217], v[18:21]
	v_mfma_f32_16x16x32_bf16 v[6:9], v[164:167], v[222:225], v[6:9]
	v_mfma_f32_16x16x32_bf16 v[2:5], v[172:175], v[222:225], v[2:5]
	s_setprio 0
	s_barrier
	s_add_i32 s45, 0, 0x18000
	s_add_i32 s46, 0, 0x1c000
	v_add_u32_e32 v156, s45, v145
	v_add_u32_e32 v172, s46, v145
	ds_read_b128 v[140:143], v156
	ds_read_b128 v[148:151], v156 offset:1024
	ds_read_b128 v[152:155], v156 offset:2048
	ds_read_b128 v[156:159], v156 offset:3072
	ds_read_b128 v[160:163], v172
	ds_read_b128 v[164:167], v172 offset:1024
	ds_read_b128 v[168:171], v172 offset:2048
	ds_read_b128 v[172:175], v172 offset:3072
	s_add_u32 s18, s18, 0x80000
	s_addc_u32 s19, s19, 0
	s_mov_b32 m0, s22
	ds_read_b128 v[180:183], v147 offset:32768
	ds_read_b128 v[184:187], v147 offset:33792
	ds_read_b128 v[202:205], v147 offset:34816
	ds_read_b128 v[206:209], v147 offset:35840
	ds_read_b128 v[210:213], v147 offset:36864
	ds_read_b128 v[214:217], v147 offset:37888
	ds_read_b128 v[218:221], v147 offset:38912
	ds_read_b128 v[222:225], v147 offset:39936
	global_load_lds_dwordx4 v134, s[18:19]
	s_mov_b32 m0, s28
	s_nop 0
	global_load_lds_dwordx4 v132, s[18:19]
	s_waitcnt vmcnt(8)
	s_waitcnt lgkmcnt(0)
	s_barrier
	s_setprio 1
	s_waitcnt lgkmcnt(0)
	v_mfma_f32_16x16x32_bf16 v[126:129], v[140:143], v[180:183], v[126:129]
	v_mfma_f32_16x16x32_bf16 v[122:125], v[152:155], v[180:183], v[122:125]
	v_mfma_f32_16x16x32_bf16 v[110:113], v[140:143], v[202:205], v[110:113]
	v_mfma_f32_16x16x32_bf16 v[106:109], v[152:155], v[202:205], v[106:109]
	v_mfma_f32_16x16x32_bf16 v[94:97], v[140:143], v[210:213], v[94:97]
	v_mfma_f32_16x16x32_bf16 v[90:93], v[152:155], v[210:213], v[90:93]
	v_mfma_f32_16x16x32_bf16 v[78:81], v[140:143], v[218:221], v[78:81]
	v_mfma_f32_16x16x32_bf16 v[74:77], v[152:155], v[218:221], v[74:77]
	v_mfma_f32_16x16x32_bf16 v[126:129], v[148:151], v[184:187], v[126:129]
	v_mfma_f32_16x16x32_bf16 v[122:125], v[156:159], v[184:187], v[122:125]
	v_mfma_f32_16x16x32_bf16 v[110:113], v[148:151], v[206:209], v[110:113]
	v_mfma_f32_16x16x32_bf16 v[106:109], v[156:159], v[206:209], v[106:109]
	v_mfma_f32_16x16x32_bf16 v[94:97], v[148:151], v[214:217], v[94:97]
	v_mfma_f32_16x16x32_bf16 v[90:93], v[156:159], v[214:217], v[90:93]
	v_mfma_f32_16x16x32_bf16 v[78:81], v[148:151], v[222:225], v[78:81]
	v_mfma_f32_16x16x32_bf16 v[74:77], v[156:159], v[222:225], v[74:77]
	s_setprio 0
	s_setprio 1
	v_mfma_f32_16x16x32_bf16 v[118:121], v[160:163], v[180:183], v[118:121]
	v_mfma_f32_16x16x32_bf16 v[114:117], v[168:171], v[180:183], v[114:117]
	v_mfma_f32_16x16x32_bf16 v[102:105], v[160:163], v[202:205], v[102:105]
	v_mfma_f32_16x16x32_bf16 v[98:101], v[168:171], v[202:205], v[98:101]
	v_mfma_f32_16x16x32_bf16 v[86:89], v[160:163], v[210:213], v[86:89]
	v_mfma_f32_16x16x32_bf16 v[82:85], v[168:171], v[210:213], v[82:85]
	v_mfma_f32_16x16x32_bf16 v[70:73], v[160:163], v[218:221], v[70:73]
	v_mfma_f32_16x16x32_bf16 v[66:69], v[168:171], v[218:221], v[66:69]
	v_mfma_f32_16x16x32_bf16 v[118:121], v[164:167], v[184:187], v[118:121]
	v_mfma_f32_16x16x32_bf16 v[114:117], v[172:175], v[184:187], v[114:117]
	v_mfma_f32_16x16x32_bf16 v[102:105], v[164:167], v[206:209], v[102:105]
	v_mfma_f32_16x16x32_bf16 v[98:101], v[172:175], v[206:209], v[98:101]
	v_mfma_f32_16x16x32_bf16 v[86:89], v[164:167], v[214:217], v[86:89]
	v_mfma_f32_16x16x32_bf16 v[82:85], v[172:175], v[214:217], v[82:85]
	v_mfma_f32_16x16x32_bf16 v[70:73], v[164:167], v[222:225], v[70:73]
	v_mfma_f32_16x16x32_bf16 v[66:69], v[172:175], v[222:225], v[66:69]
	s_setprio 0
	s_barrier
; #define PG8_STAGE(bufoff, gbase, voff) do { _Pragma("unroll") for (int _i = 0; _i < 2; ++_i) \
;         __builtin_amdgcn_global_load_lds((const unsigned*)((const char*)(gbase) + (voff)[_i]), (PG8_LAS unsigned*)(lds + (bufoff) + ldsw + _i * 8192), 16, 0, 0); } while (0)
; #define PG8_LDA(dst, b, h) do { _Pragma("unroll") for (int m = 0; m < 4; ++m) _Pragma("unroll") for (int k = 0; k < 2; ++k) dst[m][k] = *(const PG8_LAS bf16x8*)(lds + PG8_SA(b, h) + aoff + m * 2048 + k * 1024); } while (0)
; #define PG8_MMA(ai, bj, At, Bt) do { __builtin_amdgcn_s_setprio(1); _Pragma("unroll") for (int m = 0; m < 4; ++m) _Pragma("unroll") for (int n = 0; n < 2; ++n) _Pragma("unroll") for (int k = 0; k < 2; ++k) \
;         acc[ai][bj][m][n] = __builtin_amdgcn_mfma_f32_16x16x32_bf16(Bt[n][k], At[m][k], acc[ai][bj][m][n], 0, 0, 0); __builtin_amdgcn_s_setprio(0); } while (0)
; #define PG8_WAIT_V(n) asm volatile("s_waitcnt vmcnt(" #n ")" ::: "memory")
; #define PG8_WAIT_L(n) asm volatile("s_waitcnt lgkmcnt(" #n ")" ::: "memory")
; #define PG8_BAR __builtin_amdgcn_s_barrier()
; #define PG8_SCHED __builtin_amdgcn_sched_barrier(0)
; template <class Epi, class Sched, bool ALIGN_EPI = false, bool SP2 = false>
; __device__ __forceinline__ void gemm_phase(PG8_LAS unsigned char* lds, const Gemm g, const Sched& S, const Epi& E) {
;     ...
;             PG8_WAIT_V(8); PG8_WAIT_L(0); PG8_BAR; PG8_MMA(0, 0, At, B0); PG8_MMA(0, 1, At, B1); PG8_BAR; PG8_SCHED;
;             PG8_LDA(At, 1, 1); PG8_STAGE(PG8_SB(1, 0), b3, voffB); PG8_STAGE(PG8_SB(1, 1), b3 + hstep, voffB); PG8_STAGE(PG8_SA(1, 0), a3, voffA);
;             PG8_WAIT_V(8); PG8_WAIT_L(0); PG8_BAR; PG8_MMA(1, 0, At, B0); PG8_MMA(1, 1, At, B1); PG8_BAR; PG8_SCHED;
	s_add_i32 s18, s45, s0
	v_lshl_add_u64 v[176:177], v[176:177], 0, s[36:37]
	s_mov_b32 m0, s18
	ds_read_b128 v[180:183], v147 offset:49152
	ds_read_b128 v[184:187], v147 offset:50176
	ds_read_b128 v[202:205], v147 offset:51200
	ds_read_b128 v[206:209], v147 offset:52224
	ds_read_b128 v[210:213], v147 offset:53248
	ds_read_b128 v[214:217], v147 offset:54272
	ds_read_b128 v[218:221], v147 offset:55296
	ds_read_b128 v[222:225], v147 offset:56320
	global_load_lds_dwordx4 v[176:177], off
	s_add_i32 m0, s18, 0x2000
	s_add_u32 s16, s16, 0x80080
	v_lshl_add_u64 v[176:177], v[188:189], 0, s[36:37]
	s_addc_u32 s17, s17, 0
	s_add_i32 s18, s46, s0
	global_load_lds_dwordx4 v[176:177], off
	s_mov_b32 m0, s18
	s_nop 0
	global_load_lds_dwordx4 v0, s[16:17]
	s_add_i32 m0, s18, 0x2000
	s_nop 0
	global_load_lds_dwordx4 v130, s[16:17]
	v_lshl_add_u64 v[176:177], v[226:227], 0, s[36:37]
	s_mov_b32 m0, s29
	s_nop 0
	global_load_lds_dwordx4 v[176:177], off
	v_lshl_add_u64 v[176:177], v[228:229], 0, s[36:37]
	s_mov_b32 m0, s30
	s_nop 0
	global_load_lds_dwordx4 v[176:177], off
	s_waitcnt vmcnt(8)
	s_waitcnt lgkmcnt(0)
	s_barrier
	s_setprio 1
	s_waitcnt lgkmcnt(0)
	v_mfma_f32_16x16x32_bf16 v[62:65], v[140:143], v[180:183], v[62:65]
	v_mfma_f32_16x16x32_bf16 v[58:61], v[152:155], v[180:183], v[58:61]
	v_mfma_f32_16x16x32_bf16 v[46:49], v[140:143], v[202:205], v[46:49]
	v_mfma_f32_16x16x32_bf16 v[42:45], v[152:155], v[202:205], v[42:45]
	v_mfma_f32_16x16x32_bf16 v[30:33], v[140:143], v[210:213], v[30:33]
	v_mfma_f32_16x16x32_bf16 v[26:29], v[152:155], v[210:213], v[26:29]
	v_mfma_f32_16x16x32_bf16 v[14:17], v[140:143], v[218:221], v[14:17]
	v_mfma_f32_16x16x32_bf16 v[10:13], v[152:155], v[218:221], v[10:13]
	v_mfma_f32_16x16x32_bf16 v[62:65], v[148:151], v[184:187], v[62:65]
	v_mfma_f32_16x16x32_bf16 v[58:61], v[156:159], v[184:187], v[58:61]
	v_mfma_f32_16x16x32_bf16 v[46:49], v[148:151], v[206:209], v[46:49]
	v_mfma_f32_16x16x32_bf16 v[42:45], v[156:159], v[206:209], v[42:45]
	v_mfma_f32_16x16x32_bf16 v[30:33], v[148:151], v[214:217], v[30:33]
	v_mfma_f32_16x16x32_bf16 v[26:29], v[156:159], v[214:217], v[26:29]
	v_mfma_f32_16x16x32_bf16 v[14:17], v[148:151], v[222:225], v[14:17]
	v_mfma_f32_16x16x32_bf16 v[10:13], v[156:159], v[222:225], v[10:13]
	s_setprio 0
	s_setprio 1
	v_mfma_f32_16x16x32_bf16 v[54:57], v[160:163], v[180:183], v[54:57]
	v_mfma_f32_16x16x32_bf16 v[50:53], v[168:171], v[180:183], v[50:53]
	v_mfma_f32_16x16x32_bf16 v[38:41], v[160:163], v[202:205], v[38:41]
	v_mfma_f32_16x16x32_bf16 v[34:37], v[168:171], v[202:205], v[34:37]
	v_mfma_f32_16x16x32_bf16 v[22:25], v[160:163], v[210:213], v[22:25]
	v_mfma_f32_16x16x32_bf16 v[18:21], v[168:171], v[210:213], v[18:21]
	v_mfma_f32_16x16x32_bf16 v[6:9], v[160:163], v[218:221], v[6:9]
	v_mfma_f32_16x16x32_bf16 v[2:5], v[168:171], v[218:221], v[2:5]
	v_mfma_f32_16x16x32_bf16 v[54:57], v[164:167], v[184:187], v[54:57]
	v_mfma_f32_16x16x32_bf16 v[50:53], v[172:175], v[184:187], v[50:53]
	v_mfma_f32_16x16x32_bf16 v[38:41], v[164:167], v[206:209], v[38:41]
	v_mfma_f32_16x16x32_bf16 v[34:37], v[172:175], v[206:209], v[34:37]
	v_mfma_f32_16x16x32_bf16 v[22:25], v[164:167], v[214:217], v[22:25]
	v_mfma_f32_16x16x32_bf16 v[18:21], v[172:175], v[214:217], v[18:21]
	v_mfma_f32_16x16x32_bf16 v[6:9], v[164:167], v[222:225], v[6:9]
	v_mfma_f32_16x16x32_bf16 v[2:5], v[172:175], v[222:225], v[2:5]
	s_setprio 0
	s_barrier
	s_add_i32 s44, s44, 2
	s_add_u32 s24, s24, 0x100
	s_addc_u32 s25, s25, 0
	s_add_u32 s40, s40, 0x100
	s_addc_u32 s41, s41, 0
	s_cmp_gt_u32 s44, 29
	s_cbranch_scc0 .LBB0_100
	s_and_b64 vcc, exec, s[6:7]
	s_cbranch_vccz .LBB0_103
	s_barrier

; #define PG8_STAGE(bufoff, gbase, voff) do { _Pragma("unroll") for (int _i = 0; _i < 2; ++_i) \
;         __builtin_amdgcn_global_load_lds((const unsigned*)((const char*)(gbase) + (voff)[_i]), (PG8_LAS unsigned*)(lds + (bufoff) + ldsw + _i * 8192), 16, 0, 0); } while (0)
; #define PG8_LDA(dst, b, h) do { _Pragma("unroll") for (int m = 0; m < 4; ++m) _Pragma("unroll") for (int k = 0; k < 2; ++k) dst[m][k] = *(const PG8_LAS bf16x8*)(lds + PG8_SA(b, h) + aoff + m * 2048 + k * 1024); } while (0)
; #define PG8_LDB(dst, b, h) do { _Pragma("unroll") for (int n = 0; n < 2; ++n) _Pragma("unroll") for (int k = 0; k < 2; ++k) dst[n][k] = *(const PG8_LAS bf16x8*)(lds + PG8_SB(b, h) + boff + n * 2048 + k * 1024); } while (0)
; #define PG8_MMA(ai, bj, At, Bt) do { __builtin_amdgcn_s_setprio(1); _Pragma("unroll") for (int m = 0; m < 4; ++m) _Pragma("unroll") for (int n = 0; n < 2; ++n) _Pragma("unroll") for (int k = 0; k < 2; ++k) \
;         acc[ai][bj][m][n] = __builtin_amdgcn_mfma_f32_16x16x32_bf16(Bt[n][k], At[m][k], acc[ai][bj][m][n], 0, 0, 0); __builtin_amdgcn_s_setprio(0); } while (0)
; #define PG8_WAIT_V(n) asm volatile("s_waitcnt vmcnt(" #n ")" ::: "memory")
; #define PG8_WAIT_L(n) asm volatile("s_waitcnt lgkmcnt(" #n ")" ::: "memory")
; #define PG8_BAR __builtin_amdgcn_s_barrier()
; #define PG8_SCHED __builtin_amdgcn_sched_barrier(0)
; template <class Epi, class Sched, bool ALIGN_EPI = false, bool SP2 = false>
; __device__ __forceinline__ void gemm_phase(PG8_LAS unsigned char* lds, const Gemm g, const Sched& S, const Epi& E) {
;     ...
;             PG8_LDB(B0, 0, 0); PG8_LDB(B1, 0, 1); PG8_SCHED; PG8_LDA(At, 0, 0); PG8_STAGE(PG8_SA(1, 1), a1 + hstep, voffA);
;             PG8_WAIT_V(8); PG8_WAIT_L(0); PG8_BAR; PG8_MMA(0, 0, At, B0); PG8_MMA(0, 1, At, B1); PG8_BAR; PG8_SCHED;
;             PG8_LDA(At, 0, 1); PG8_STAGE(PG8_SB(0, 0), b2, voffB); PG8_STAGE(PG8_SB(0, 1), b2 + hstep, voffB); PG8_STAGE(PG8_SA(0, 0), a2, voffA);
;             PG8_WAIT_V(8); PG8_WAIT_L(0); PG8_BAR; PG8_MMA(1, 0, At, B0); PG8_MMA(1, 1, At, B1); PG8_BAR; PG8_SCHED;
.LBB0_179:
	s_add_i32 s30, s12, 2
	s_add_u32 s31, s10, 0x80
	s_addc_u32 s13, s11, 0
	s_add_i32 s38, 0, 0x10000
	s_cmp_eq_u32 s41, s12
	s_cselect_b32 s13, s7, s13
	s_cselect_b32 s12, s6, s31
	s_cselect_b32 s35, s9, s29
	s_cselect_b32 s34, s8, s28
	s_add_i32 s31, 0, 0x14000
	v_add_u32_e32 v148, s38, v157
	v_add_u32_e32 v168, s31, v157
	ds_read_b128 v[130:133], v148
	ds_read_b128 v[134:137], v148 offset:1024
	ds_read_b128 v[138:141], v148 offset:2048
	ds_read_b128 v[148:151], v148 offset:3072
	ds_read_b128 v[152:155], v168
	ds_read_b128 v[160:163], v168 offset:1024
	ds_read_b128 v[164:167], v168 offset:2048
	ds_read_b128 v[168:171], v168 offset:3072
	v_lshl_add_u64 v[176:177], s[10:11], 0, v[144:145]
	s_add_i32 m0, s1, 0xc000
	ds_read_b128 v[172:175], v159
	ds_read_b128 v[180:183], v159 offset:1024
	ds_read_b128 v[184:187], v159 offset:2048
	ds_read_b128 v[202:205], v159 offset:3072
	ds_read_b128 v[206:209], v159 offset:4096
	ds_read_b128 v[210:213], v159 offset:5120
	ds_read_b128 v[214:217], v159 offset:6144
	ds_read_b128 v[218:221], v159 offset:7168
	global_load_lds_dwordx4 v[176:177], off
	v_lshl_add_u64 v[176:177], s[10:11], 0, v[146:147]
	s_add_i32 m0, s1, 0xe000
	s_nop 0
	global_load_lds_dwordx4 v[176:177], off
	s_waitcnt vmcnt(8)
	s_waitcnt lgkmcnt(0)
	s_barrier
	s_setprio 1
	s_waitcnt lgkmcnt(0)
	v_mfma_f32_16x16x32_bf16 v[126:129], v[130:133], v[172:175], v[126:129]
	v_mfma_f32_16x16x32_bf16 v[122:125], v[138:141], v[172:175], v[122:125]
	v_mfma_f32_16x16x32_bf16 v[118:121], v[130:133], v[184:187], v[118:121]
	v_mfma_f32_16x16x32_bf16 v[106:109], v[138:141], v[184:187], v[106:109]
	v_mfma_f32_16x16x32_bf16 v[102:105], v[130:133], v[206:209], v[102:105]
	v_mfma_f32_16x16x32_bf16 v[90:93], v[138:141], v[206:209], v[90:93]
	v_mfma_f32_16x16x32_bf16 v[86:89], v[130:133], v[214:217], v[86:89]
	v_mfma_f32_16x16x32_bf16 v[74:77], v[138:141], v[214:217], v[74:77]
	v_mfma_f32_16x16x32_bf16 v[126:129], v[134:137], v[180:183], v[126:129]
	v_mfma_f32_16x16x32_bf16 v[122:125], v[148:151], v[180:183], v[122:125]
	v_mfma_f32_16x16x32_bf16 v[118:121], v[134:137], v[202:205], v[118:121]
	v_mfma_f32_16x16x32_bf16 v[106:109], v[148:151], v[202:205], v[106:109]
	v_mfma_f32_16x16x32_bf16 v[102:105], v[134:137], v[210:213], v[102:105]
	v_mfma_f32_16x16x32_bf16 v[90:93], v[148:151], v[210:213], v[90:93]
	v_mfma_f32_16x16x32_bf16 v[86:89], v[134:137], v[218:221], v[86:89]
	v_mfma_f32_16x16x32_bf16 v[74:77], v[148:151], v[218:221], v[74:77]
	s_setprio 0
	s_setprio 1
	v_mfma_f32_16x16x32_bf16 v[114:117], v[152:155], v[172:175], v[114:117]
	v_mfma_f32_16x16x32_bf16 v[110:113], v[164:167], v[172:175], v[110:113]
	v_mfma_f32_16x16x32_bf16 v[98:101], v[152:155], v[184:187], v[98:101]
	v_mfma_f32_16x16x32_bf16 v[94:97], v[164:167], v[184:187], v[94:97]
	v_mfma_f32_16x16x32_bf16 v[82:85], v[152:155], v[206:209], v[82:85]
	v_mfma_f32_16x16x32_bf16 v[78:81], v[164:167], v[206:209], v[78:81]
	v_mfma_f32_16x16x32_bf16 v[70:73], v[152:155], v[214:217], v[70:73]
	v_mfma_f32_16x16x32_bf16 v[66:69], v[164:167], v[214:217], v[66:69]
	v_mfma_f32_16x16x32_bf16 v[114:117], v[160:163], v[180:183], v[114:117]
	v_mfma_f32_16x16x32_bf16 v[110:113], v[168:171], v[180:183], v[110:113]
	v_mfma_f32_16x16x32_bf16 v[98:101], v[160:163], v[202:205], v[98:101]
	v_mfma_f32_16x16x32_bf16 v[94:97], v[168:171], v[202:205], v[94:97]
	v_mfma_f32_16x16x32_bf16 v[82:85], v[160:163], v[210:213], v[82:85]
	v_mfma_f32_16x16x32_bf16 v[78:81], v[168:171], v[210:213], v[78:81]
	v_mfma_f32_16x16x32_bf16 v[70:73], v[160:163], v[218:221], v[70:73]
	v_mfma_f32_16x16x32_bf16 v[66:69], v[168:171], v[218:221], v[66:69]
	s_setprio 0
	s_barrier
	s_add_i32 s38, s38, s0
	v_lshl_add_u64 v[176:177], s[34:35], 0, v[0:1]
	s_mov_b32 m0, s38
	ds_read_b128 v[172:175], v159 offset:16384
	ds_read_b128 v[180:183], v159 offset:17408
	ds_read_b128 v[184:187], v159 offset:18432
	ds_read_b128 v[202:205], v159 offset:19456
	ds_read_b128 v[206:209], v159 offset:20480
	ds_read_b128 v[210:213], v159 offset:21504
	ds_read_b128 v[214:217], v159 offset:22528
	ds_read_b128 v[218:221], v159 offset:23552
	global_load_lds_dwordx4 v[176:177], off
	s_add_i32 m0, s38, 0x2000
	v_lshl_add_u64 v[188:189], s[34:35], 0, v[142:143]
	s_add_u32 s34, s34, s44
	s_addc_u32 s35, s35, 0
	s_add_i32 s31, s31, s0
	global_load_lds_dwordx4 v[188:189], off
	v_lshl_add_u64 v[222:223], s[34:35], 0, v[0:1]
	s_mov_b32 m0, s31
	v_lshl_add_u64 v[224:225], s[34:35], 0, v[142:143]
	global_load_lds_dwordx4 v[222:223], off
	s_add_i32 m0, s31, 0x2000
	v_lshl_add_u64 v[226:227], s[12:13], 0, v[0:1]
	global_load_lds_dwordx4 v[224:225], off
	s_mov_b32 m0, s1
	v_lshl_add_u64 v[228:229], s[12:13], 0, v[142:143]
	global_load_lds_dwordx4 v[226:227], off
	s_mov_b32 m0, s14
	s_nop 0
	global_load_lds_dwordx4 v[228:229], off
	s_waitcnt vmcnt(8)
	s_waitcnt lgkmcnt(0)
	s_barrier
; #define PG8_STAGE(bufoff, gbase, voff) do { _Pragma("unroll") for (int _i = 0; _i < 2; ++_i) \
;         __builtin_amdgcn_global_load_lds((const unsigned*)((const char*)(gbase) + (voff)[_i]), (PG8_LAS unsigned*)(lds + (bufoff) + ldsw + _i * 8192), 16, 0, 0); } while (0)
; #define PG8_LDA(dst, b, h) do { _Pragma("unroll") for (int m = 0; m < 4; ++m) _Pragma("unroll") for (int k = 0; k < 2; ++k) dst[m][k] = *(const PG8_LAS bf16x8*)(lds + PG8_SA(b, h) + aoff + m * 2048 + k * 1024); } while (0)
; #define PG8_LDB(dst, b, h) do { _Pragma("unroll") for (int n = 0; n < 2; ++n) _Pragma("unroll") for (int k = 0; k < 2; ++k) dst[n][k] = *(const PG8_LAS bf16x8*)(lds + PG8_SB(b, h) + boff + n * 2048 + k * 1024); } while (0)
; #define PG8_MMA(ai, bj, At, Bt) do { __builtin_amdgcn_s_setprio(1); _Pragma("unroll") for (int m = 0; m < 4; ++m) _Pragma("unroll") for (int n = 0; n < 2; ++n) _Pragma("unroll") for (int k = 0; k < 2; ++k) \
;         acc[ai][bj][m][n] = __builtin_amdgcn_mfma_f32_16x16x32_bf16(Bt[n][k], At[m][k], acc[ai][bj][m][n], 0, 0, 0); __builtin_amdgcn_s_setprio(0); } while (0)
; #define PG8_WAIT_V(n) asm volatile("s_waitcnt vmcnt(" #n ")" ::: "memory")
; #define PG8_WAIT_L(n) asm volatile("s_waitcnt lgkmcnt(" #n ")" ::: "memory")
; #define PG8_BAR __builtin_amdgcn_s_barrier()
; #define PG8_SCHED __builtin_amdgcn_sched_barrier(0)
; template <class Epi, class Sched, bool ALIGN_EPI = false, bool SP2 = false>
; __device__ __forceinline__ void gemm_phase(PG8_LAS unsigned char* lds, const Gemm g, const Sched& S, const Epi& E) {
;     ...
;             PG8_WAIT_V(8); PG8_WAIT_L(0); PG8_BAR; PG8_MMA(1, 0, At, B0); PG8_MMA(1, 1, At, B1); PG8_BAR; PG8_SCHED;
;             PG8_LDB(B0, 1, 0); PG8_LDB(B1, 1, 1); PG8_SCHED; PG8_LDA(At, 1, 0); PG8_STAGE(PG8_SA(0, 1), a2 + hstep, voffA);
;             PG8_WAIT_V(8); PG8_WAIT_L(0); PG8_BAR; PG8_MMA(0, 0, At, B0); PG8_MMA(0, 1, At, B1); PG8_BAR; PG8_SCHED;
;             PG8_LDA(At, 1, 1); PG8_STAGE(PG8_SB(1, 0), b3, voffB); PG8_STAGE(PG8_SB(1, 1), b3 + hstep, voffB); PG8_STAGE(PG8_SA(1, 0), a3, voffA);
	s_setprio 1
	s_waitcnt lgkmcnt(0)
	v_mfma_f32_16x16x32_bf16 v[62:65], v[130:133], v[172:175], v[62:65]
	v_mfma_f32_16x16x32_bf16 v[58:61], v[138:141], v[172:175], v[58:61]
	v_mfma_f32_16x16x32_bf16 v[54:57], v[130:133], v[184:187], v[54:57]
	v_mfma_f32_16x16x32_bf16 v[42:45], v[138:141], v[184:187], v[42:45]
	v_mfma_f32_16x16x32_bf16 v[38:41], v[130:133], v[206:209], v[38:41]
	v_mfma_f32_16x16x32_bf16 v[26:29], v[138:141], v[206:209], v[26:29]
	v_mfma_f32_16x16x32_bf16 v[22:25], v[130:133], v[214:217], v[22:25]
	v_mfma_f32_16x16x32_bf16 v[10:13], v[138:141], v[214:217], v[10:13]
	v_mfma_f32_16x16x32_bf16 v[62:65], v[134:137], v[180:183], v[62:65]
	v_mfma_f32_16x16x32_bf16 v[58:61], v[148:151], v[180:183], v[58:61]
	v_mfma_f32_16x16x32_bf16 v[54:57], v[134:137], v[202:205], v[54:57]
	v_mfma_f32_16x16x32_bf16 v[42:45], v[148:151], v[202:205], v[42:45]
	v_mfma_f32_16x16x32_bf16 v[38:41], v[134:137], v[210:213], v[38:41]
	v_mfma_f32_16x16x32_bf16 v[26:29], v[148:151], v[210:213], v[26:29]
	v_mfma_f32_16x16x32_bf16 v[22:25], v[134:137], v[218:221], v[22:25]
	v_mfma_f32_16x16x32_bf16 v[10:13], v[148:151], v[218:221], v[10:13]
	s_setprio 0
	s_setprio 1
	v_mfma_f32_16x16x32_bf16 v[50:53], v[152:155], v[172:175], v[50:53]
	v_mfma_f32_16x16x32_bf16 v[46:49], v[164:167], v[172:175], v[46:49]
	v_mfma_f32_16x16x32_bf16 v[34:37], v[152:155], v[184:187], v[34:37]
	v_mfma_f32_16x16x32_bf16 v[30:33], v[164:167], v[184:187], v[30:33]
	v_mfma_f32_16x16x32_bf16 v[18:21], v[152:155], v[206:209], v[18:21]
	v_mfma_f32_16x16x32_bf16 v[14:17], v[164:167], v[206:209], v[14:17]
	v_mfma_f32_16x16x32_bf16 v[6:9], v[152:155], v[214:217], v[6:9]
	v_mfma_f32_16x16x32_bf16 v[2:5], v[164:167], v[214:217], v[2:5]
	v_mfma_f32_16x16x32_bf16 v[50:53], v[160:163], v[180:183], v[50:53]
	v_mfma_f32_16x16x32_bf16 v[46:49], v[168:171], v[180:183], v[46:49]
	v_mfma_f32_16x16x32_bf16 v[34:37], v[160:163], v[202:205], v[34:37]
	v_mfma_f32_16x16x32_bf16 v[30:33], v[168:171], v[202:205], v[30:33]
	v_mfma_f32_16x16x32_bf16 v[18:21], v[160:163], v[210:213], v[18:21]
	v_mfma_f32_16x16x32_bf16 v[14:17], v[168:171], v[210:213], v[14:17]
	v_mfma_f32_16x16x32_bf16 v[6:9], v[160:163], v[218:221], v[6:9]
	v_mfma_f32_16x16x32_bf16 v[2:5], v[168:171], v[218:221], v[2:5]
	s_setprio 0
	s_barrier
	s_add_i32 s31, 0, 0x18000
	s_add_i32 s34, 0, 0x1c000
	v_add_u32_e32 v148, s31, v157
	v_add_u32_e32 v168, s34, v157
	ds_read_b128 v[130:133], v148
	ds_read_b128 v[134:137], v148 offset:1024
	ds_read_b128 v[138:141], v148 offset:2048
	ds_read_b128 v[148:151], v148 offset:3072
	ds_read_b128 v[152:155], v168
	ds_read_b128 v[160:163], v168 offset:1024
	ds_read_b128 v[164:167], v168 offset:2048
	ds_read_b128 v[168:171], v168 offset:3072
	s_add_u32 s12, s12, s44
	s_addc_u32 s13, s13, 0
	s_mov_b32 m0, s16
	ds_read_b128 v[172:175], v159 offset:32768
	ds_read_b128 v[180:183], v159 offset:33792
	ds_read_b128 v[184:187], v159 offset:34816
	ds_read_b128 v[202:205], v159 offset:35840
	ds_read_b128 v[206:209], v159 offset:36864
	ds_read_b128 v[210:213], v159 offset:37888
	ds_read_b128 v[214:217], v159 offset:38912
	ds_read_b128 v[218:221], v159 offset:39936
	global_load_lds_dwordx4 v0, s[12:13]
	s_mov_b32 m0, s17
	s_nop 0
	global_load_lds_dwordx4 v142, s[12:13]
	s_waitcnt vmcnt(8)
	s_waitcnt lgkmcnt(0)
	s_barrier
	s_setprio 1
	s_waitcnt lgkmcnt(0)
	v_mfma_f32_16x16x32_bf16 v[126:129], v[130:133], v[172:175], v[126:129]
	v_mfma_f32_16x16x32_bf16 v[122:125], v[138:141], v[172:175], v[122:125]
	v_mfma_f32_16x16x32_bf16 v[118:121], v[130:133], v[184:187], v[118:121]
	v_mfma_f32_16x16x32_bf16 v[106:109], v[138:141], v[184:187], v[106:109]
	v_mfma_f32_16x16x32_bf16 v[102:105], v[130:133], v[206:209], v[102:105]
	v_mfma_f32_16x16x32_bf16 v[90:93], v[138:141], v[206:209], v[90:93]
	v_mfma_f32_16x16x32_bf16 v[86:89], v[130:133], v[214:217], v[86:89]
	v_mfma_f32_16x16x32_bf16 v[74:77], v[138:141], v[214:217], v[74:77]
	v_mfma_f32_16x16x32_bf16 v[126:129], v[134:137], v[180:183], v[126:129]
	v_mfma_f32_16x16x32_bf16 v[122:125], v[148:151], v[180:183], v[122:125]
	v_mfma_f32_16x16x32_bf16 v[118:121], v[134:137], v[202:205], v[118:121]
	v_mfma_f32_16x16x32_bf16 v[106:109], v[148:151], v[202:205], v[106:109]
	v_mfma_f32_16x16x32_bf16 v[102:105], v[134:137], v[210:213], v[102:105]
	v_mfma_f32_16x16x32_bf16 v[90:93], v[148:151], v[210:213], v[90:93]
	v_mfma_f32_16x16x32_bf16 v[86:89], v[134:137], v[218:221], v[86:89]
	v_mfma_f32_16x16x32_bf16 v[74:77], v[148:151], v[218:221], v[74:77]
	s_setprio 0
	s_setprio 1
	v_mfma_f32_16x16x32_bf16 v[114:117], v[152:155], v[172:175], v[114:117]
	v_mfma_f32_16x16x32_bf16 v[110:113], v[164:167], v[172:175], v[110:113]
	v_mfma_f32_16x16x32_bf16 v[98:101], v[152:155], v[184:187], v[98:101]
	v_mfma_f32_16x16x32_bf16 v[94:97], v[164:167], v[184:187], v[94:97]
	v_mfma_f32_16x16x32_bf16 v[82:85], v[152:155], v[206:209], v[82:85]
	v_mfma_f32_16x16x32_bf16 v[78:81], v[164:167], v[206:209], v[78:81]
	v_mfma_f32_16x16x32_bf16 v[70:73], v[152:155], v[214:217], v[70:73]
	v_mfma_f32_16x16x32_bf16 v[66:69], v[164:167], v[214:217], v[66:69]
	v_mfma_f32_16x16x32_bf16 v[114:117], v[160:163], v[180:183], v[114:117]
	v_mfma_f32_16x16x32_bf16 v[110:113], v[168:171], v[180:183], v[110:113]
	v_mfma_f32_16x16x32_bf16 v[98:101], v[160:163], v[202:205], v[98:101]
	v_mfma_f32_16x16x32_bf16 v[94:97], v[168:171], v[202:205], v[94:97]
	v_mfma_f32_16x16x32_bf16 v[82:85], v[160:163], v[210:213], v[82:85]
	v_mfma_f32_16x16x32_bf16 v[78:81], v[168:171], v[210:213], v[78:81]
	v_mfma_f32_16x16x32_bf16 v[70:73], v[160:163], v[218:221], v[70:73]
	v_mfma_f32_16x16x32_bf16 v[66:69], v[168:171], v[218:221], v[66:69]
	s_setprio 0
	s_barrier
; #define PG8_STAGE(bufoff, gbase, voff) do { _Pragma("unroll") for (int _i = 0; _i < 2; ++_i) \
;         __builtin_amdgcn_global_load_lds((const unsigned*)((const char*)(gbase) + (voff)[_i]), (PG8_LAS unsigned*)(lds + (bufoff) + ldsw + _i * 8192), 16, 0, 0); } while (0)
; #define PG8_LDA(dst, b, h) do { _Pragma("unroll") for (int m = 0; m < 4; ++m) _Pragma("unroll") for (int k = 0; k < 2; ++k) dst[m][k] = *(const PG8_LAS bf16x8*)(lds + PG8_SA(b, h) + aoff + m * 2048 + k * 1024); } while (0)
; #define PG8_MMA(ai, bj, At, Bt) do { __builtin_amdgcn_s_setprio(1); _Pragma("unroll") for (int m = 0; m < 4; ++m) _Pragma("unroll") for (int n = 0; n < 2; ++n) _Pragma("unroll") for (int k = 0; k < 2; ++k) \
;         acc[ai][bj][m][n] = __builtin_amdgcn_mfma_f32_16x16x32_bf16(Bt[n][k], At[m][k], acc[ai][bj][m][n], 0, 0, 0); __builtin_amdgcn_s_setprio(0); } while (0)
; #define PG8_WAIT_V(n) asm volatile("s_waitcnt vmcnt(" #n ")" ::: "memory")
; #define PG8_WAIT_L(n) asm volatile("s_waitcnt lgkmcnt(" #n ")" ::: "memory")
; #define PG8_BAR __builtin_amdgcn_s_barrier()
; #define PG8_SCHED __builtin_amdgcn_sched_barrier(0)
; template <class Epi, class Sched, bool ALIGN_EPI = false, bool SP2 = false>
; __device__ __forceinline__ void gemm_phase(PG8_LAS unsigned char* lds, const Gemm g, const Sched& S, const Epi& E) {
;     ...
;             PG8_WAIT_V(8); PG8_WAIT_L(0); PG8_BAR; PG8_MMA(0, 0, At, B0); PG8_MMA(0, 1, At, B1); PG8_BAR; PG8_SCHED;
;             PG8_LDA(At, 1, 1); PG8_STAGE(PG8_SB(1, 0), b3, voffB); PG8_STAGE(PG8_SB(1, 1), b3 + hstep, voffB); PG8_STAGE(PG8_SA(1, 0), a3, voffA);
;             PG8_WAIT_V(8); PG8_WAIT_L(0); PG8_BAR; PG8_MMA(1, 0, At, B0); PG8_MMA(1, 1, At, B1); PG8_BAR; PG8_SCHED;
	s_add_i32 s12, s31, s0
	v_lshl_add_u64 v[176:177], v[176:177], 0, s[36:37]
	s_mov_b32 m0, s12
	ds_read_b128 v[172:175], v159 offset:49152
	ds_read_b128 v[180:183], v159 offset:50176
	ds_read_b128 v[184:187], v159 offset:51200
	ds_read_b128 v[202:205], v159 offset:52224
	ds_read_b128 v[206:209], v159 offset:53248
	ds_read_b128 v[210:213], v159 offset:54272
	ds_read_b128 v[214:217], v159 offset:55296
	ds_read_b128 v[218:221], v159 offset:56320
	global_load_lds_dwordx4 v[176:177], off
	v_lshl_add_u64 v[176:177], v[188:189], 0, s[36:37]
	s_add_i32 m0, s12, 0x2000
	s_add_i32 s12, s34, s0
	global_load_lds_dwordx4 v[176:177], off
	v_lshl_add_u64 v[176:177], v[222:223], 0, s[36:37]
	s_mov_b32 m0, s12
	s_nop 0
	global_load_lds_dwordx4 v[176:177], off
	v_lshl_add_u64 v[176:177], v[224:225], 0, s[36:37]
	s_add_i32 m0, s12, 0x2000
	s_nop 0
	global_load_lds_dwordx4 v[176:177], off
	v_lshl_add_u64 v[176:177], v[226:227], 0, s[36:37]
	s_mov_b32 m0, s18
	s_nop 0
	global_load_lds_dwordx4 v[176:177], off
	v_lshl_add_u64 v[176:177], v[228:229], 0, s[36:37]
	s_mov_b32 m0, s19
	s_nop 0
	global_load_lds_dwordx4 v[176:177], off
	s_waitcnt vmcnt(8)
	s_waitcnt lgkmcnt(0)
	s_barrier
	s_setprio 1
	s_waitcnt lgkmcnt(0)
	v_mfma_f32_16x16x32_bf16 v[62:65], v[130:133], v[172:175], v[62:65]
	v_mfma_f32_16x16x32_bf16 v[58:61], v[138:141], v[172:175], v[58:61]
	v_mfma_f32_16x16x32_bf16 v[54:57], v[130:133], v[184:187], v[54:57]
	v_mfma_f32_16x16x32_bf16 v[42:45], v[138:141], v[184:187], v[42:45]
	v_mfma_f32_16x16x32_bf16 v[38:41], v[130:133], v[206:209], v[38:41]
	v_mfma_f32_16x16x32_bf16 v[26:29], v[138:141], v[206:209], v[26:29]
	v_mfma_f32_16x16x32_bf16 v[22:25], v[130:133], v[214:217], v[22:25]
	v_mfma_f32_16x16x32_bf16 v[10:13], v[138:141], v[214:217], v[10:13]
	v_mfma_f32_16x16x32_bf16 v[62:65], v[134:137], v[180:183], v[62:65]
	v_mfma_f32_16x16x32_bf16 v[58:61], v[148:151], v[180:183], v[58:61]
	v_mfma_f32_16x16x32_bf16 v[54:57], v[134:137], v[202:205], v[54:57]
	v_mfma_f32_16x16x32_bf16 v[42:45], v[148:151], v[202:205], v[42:45]
	v_mfma_f32_16x16x32_bf16 v[38:41], v[134:137], v[210:213], v[38:41]
	v_mfma_f32_16x16x32_bf16 v[26:29], v[148:151], v[210:213], v[26:29]
	v_mfma_f32_16x16x32_bf16 v[22:25], v[134:137], v[218:221], v[22:25]
	v_mfma_f32_16x16x32_bf16 v[10:13], v[148:151], v[218:221], v[10:13]
	s_setprio 0
	s_setprio 1
	v_mfma_f32_16x16x32_bf16 v[50:53], v[152:155], v[172:175], v[50:53]
	v_mfma_f32_16x16x32_bf16 v[46:49], v[164:167], v[172:175], v[46:49]
	v_mfma_f32_16x16x32_bf16 v[34:37], v[152:155], v[184:187], v[34:37]
	v_mfma_f32_16x16x32_bf16 v[30:33], v[164:167], v[184:187], v[30:33]
	v_mfma_f32_16x16x32_bf16 v[18:21], v[152:155], v[206:209], v[18:21]
	v_mfma_f32_16x16x32_bf16 v[14:17], v[164:167], v[206:209], v[14:17]
	v_mfma_f32_16x16x32_bf16 v[6:9], v[152:155], v[214:217], v[6:9]
	v_mfma_f32_16x16x32_bf16 v[2:5], v[164:167], v[214:217], v[2:5]
	v_mfma_f32_16x16x32_bf16 v[50:53], v[160:163], v[180:183], v[50:53]
	v_mfma_f32_16x16x32_bf16 v[46:49], v[168:171], v[180:183], v[46:49]
	v_mfma_f32_16x16x32_bf16 v[34:37], v[160:163], v[202:205], v[34:37]
	v_mfma_f32_16x16x32_bf16 v[30:33], v[168:171], v[202:205], v[30:33]
	v_mfma_f32_16x16x32_bf16 v[18:21], v[160:163], v[210:213], v[18:21]
	v_mfma_f32_16x16x32_bf16 v[14:17], v[168:171], v[210:213], v[14:17]
	v_mfma_f32_16x16x32_bf16 v[6:9], v[160:163], v[218:221], v[6:9]
	v_mfma_f32_16x16x32_bf16 v[2:5], v[168:171], v[218:221], v[2:5]
	s_setprio 0
	s_barrier
	s_add_u32 s10, s10, 0x100
	s_addc_u32 s11, s11, 0
	s_add_u32 s28, s28, 0x100
	s_addc_u32 s29, s29, 0
	s_cmp_ge_u32 s30, s40
	s_mov_b32 s12, s30
	s_cbranch_scc0 .LBB0_179
	s_and_b64 vcc, exec, s[4:5]
	s_cbranch_vccz .LBB0_182
	s_barrier

; #define PG8_STAGE(bufoff, gbase, voff) do { _Pragma("unroll") for (int _i = 0; _i < 2; ++_i) \
;         __builtin_amdgcn_global_load_lds((const unsigned*)((const char*)(gbase) + (voff)[_i]), (PG8_LAS unsigned*)(lds + (bufoff) + ldsw + _i * 8192), 16, 0, 0); } while (0)
; #define PG8_LDA(dst, b, h) do { _Pragma("unroll") for (int m = 0; m < 4; ++m) _Pragma("unroll") for (int k = 0; k < 2; ++k) dst[m][k] = *(const PG8_LAS bf16x8*)(lds + PG8_SA(b, h) + aoff + m * 2048 + k * 1024); } while (0)
; #define PG8_LDB(dst, b, h) do { _Pragma("unroll") for (int n = 0; n < 2; ++n) _Pragma("unroll") for (int k = 0; k < 2; ++k) dst[n][k] = *(const PG8_LAS bf16x8*)(lds + PG8_SB(b, h) + boff + n * 2048 + k * 1024); } while (0)
; #define PG8_MMA(ai, bj, At, Bt) do { __builtin_amdgcn_s_setprio(1); _Pragma("unroll") for (int m = 0; m < 4; ++m) _Pragma("unroll") for (int n = 0; n < 2; ++n) _Pragma("unroll") for (int k = 0; k < 2; ++k) \
;         acc[ai][bj][m][n] = __builtin_amdgcn_mfma_f32_16x16x32_bf16(Bt[n][k], At[m][k], acc[ai][bj][m][n], 0, 0, 0); __builtin_amdgcn_s_setprio(0); } while (0)
; #define PG8_WAIT_V(n) asm volatile("s_waitcnt vmcnt(" #n ")" ::: "memory")
; #define PG8_WAIT_L(n) asm volatile("s_waitcnt lgkmcnt(" #n ")" ::: "memory")
; #define PG8_BAR __builtin_amdgcn_s_barrier()
; #define PG8_SCHED __builtin_amdgcn_sched_barrier(0)
; template <class Epi, class Sched, bool ALIGN_EPI = false, bool SP2 = false>
; __device__ __forceinline__ void gemm_phase(PG8_LAS unsigned char* lds, const Gemm g, const Sched& S, const Epi& E) {
;     ...
;             PG8_LDB(B0, 0, 0); PG8_LDB(B1, 0, 1); PG8_SCHED; PG8_LDA(At, 0, 0); PG8_STAGE(PG8_SA(1, 1), a1 + hstep, voffA);
;             PG8_WAIT_V(8); PG8_WAIT_L(0); PG8_BAR; PG8_MMA(0, 0, At, B0); PG8_MMA(0, 1, At, B1); PG8_BAR; PG8_SCHED;
;             PG8_LDA(At, 0, 1); PG8_STAGE(PG8_SB(0, 0), b2, voffB); PG8_STAGE(PG8_SB(0, 1), b2 + hstep, voffB); PG8_STAGE(PG8_SA(0, 0), a2, voffA);
;             PG8_WAIT_V(8); PG8_WAIT_L(0); PG8_BAR; PG8_MMA(1, 0, At, B0); PG8_MMA(1, 1, At, B1); PG8_BAR; PG8_SCHED;
.LBB0_496:
	s_add_u32 s16, s20, 0xfff80080
	s_addc_u32 s17, s21, -1
	s_add_i32 s41, 0, 0x10000
	s_cmp_eq_u32 s40, 28
	s_cselect_b32 s19, s9, s17
	s_cselect_b32 s18, s34, s16
	s_cselect_b32 s17, s7, s39
	s_cselect_b32 s16, s35, s38
	s_add_i32 s46, 0, 0x14000
	v_add_u32_e32 v156, s41, v145
	v_add_u32_e32 v172, s46, v145
	ds_read_b128 v[140:143], v156
	ds_read_b128 v[148:151], v156 offset:1024
	ds_read_b128 v[152:155], v156 offset:2048
	ds_read_b128 v[156:159], v156 offset:3072
	ds_read_b128 v[160:163], v172
	ds_read_b128 v[164:167], v172 offset:1024
	ds_read_b128 v[168:171], v172 offset:2048
	ds_read_b128 v[172:175], v172 offset:3072
	v_lshl_add_u64 v[176:177], s[20:21], 0, v[136:137]
	s_add_i32 m0, s1, 0xc000
	ds_read_b128 v[184:187], v147
	ds_read_b128 v[202:205], v147 offset:1024
	ds_read_b128 v[206:209], v147 offset:2048
	ds_read_b128 v[210:213], v147 offset:3072
	ds_read_b128 v[214:217], v147 offset:4096
	ds_read_b128 v[218:221], v147 offset:5120
	ds_read_b128 v[222:225], v147 offset:6144
	ds_read_b128 v[226:229], v147 offset:7168
	global_load_lds_dwordx4 v[176:177], off
	v_lshl_add_u64 v[176:177], s[20:21], 0, v[138:139]
	s_add_i32 m0, s1, 0xe000
	s_nop 0
	global_load_lds_dwordx4 v[176:177], off
	s_waitcnt vmcnt(8)
	s_waitcnt lgkmcnt(0)
	s_barrier
	s_setprio 1
	s_waitcnt lgkmcnt(0)
	v_mfma_f32_16x16x32_bf16 v[126:129], v[140:143], v[184:187], v[126:129]
	v_mfma_f32_16x16x32_bf16 v[122:125], v[152:155], v[184:187], v[122:125]
	v_mfma_f32_16x16x32_bf16 v[118:121], v[140:143], v[206:209], v[118:121]
	v_mfma_f32_16x16x32_bf16 v[110:113], v[152:155], v[206:209], v[110:113]
	v_mfma_f32_16x16x32_bf16 v[102:105], v[140:143], v[214:217], v[102:105]
	v_mfma_f32_16x16x32_bf16 v[94:97], v[152:155], v[214:217], v[94:97]
	v_mfma_f32_16x16x32_bf16 v[86:89], v[140:143], v[222:225], v[86:89]
	v_mfma_f32_16x16x32_bf16 v[78:81], v[152:155], v[222:225], v[78:81]
	v_mfma_f32_16x16x32_bf16 v[126:129], v[148:151], v[202:205], v[126:129]
	v_mfma_f32_16x16x32_bf16 v[122:125], v[156:159], v[202:205], v[122:125]
	v_mfma_f32_16x16x32_bf16 v[118:121], v[148:151], v[210:213], v[118:121]
	v_mfma_f32_16x16x32_bf16 v[110:113], v[156:159], v[210:213], v[110:113]
	v_mfma_f32_16x16x32_bf16 v[102:105], v[148:151], v[218:221], v[102:105]
	v_mfma_f32_16x16x32_bf16 v[94:97], v[156:159], v[218:221], v[94:97]
	v_mfma_f32_16x16x32_bf16 v[86:89], v[148:151], v[226:229], v[86:89]
	v_mfma_f32_16x16x32_bf16 v[78:81], v[156:159], v[226:229], v[78:81]
	s_setprio 0
	s_setprio 1
	v_mfma_f32_16x16x32_bf16 v[114:117], v[160:163], v[184:187], v[114:117]
	v_mfma_f32_16x16x32_bf16 v[106:109], v[168:171], v[184:187], v[106:109]
	v_mfma_f32_16x16x32_bf16 v[98:101], v[160:163], v[206:209], v[98:101]
	v_mfma_f32_16x16x32_bf16 v[90:93], v[168:171], v[206:209], v[90:93]
	v_mfma_f32_16x16x32_bf16 v[82:85], v[160:163], v[214:217], v[82:85]
	v_mfma_f32_16x16x32_bf16 v[74:77], v[168:171], v[214:217], v[74:77]
	v_mfma_f32_16x16x32_bf16 v[70:73], v[160:163], v[222:225], v[70:73]
	v_mfma_f32_16x16x32_bf16 v[66:69], v[168:171], v[222:225], v[66:69]
	v_mfma_f32_16x16x32_bf16 v[114:117], v[164:167], v[202:205], v[114:117]
	v_mfma_f32_16x16x32_bf16 v[106:109], v[172:175], v[202:205], v[106:109]
	v_mfma_f32_16x16x32_bf16 v[98:101], v[164:167], v[210:213], v[98:101]
	v_mfma_f32_16x16x32_bf16 v[90:93], v[172:175], v[210:213], v[90:93]
	v_mfma_f32_16x16x32_bf16 v[82:85], v[164:167], v[218:221], v[82:85]
	v_mfma_f32_16x16x32_bf16 v[74:77], v[172:175], v[218:221], v[74:77]
	v_mfma_f32_16x16x32_bf16 v[70:73], v[164:167], v[226:229], v[70:73]
	v_mfma_f32_16x16x32_bf16 v[66:69], v[172:175], v[226:229], v[66:69]
	s_setprio 0
	s_barrier
	s_add_i32 s41, s41, s0
	v_lshl_add_u64 v[176:177], s[16:17], 0, v[0:1]
	s_mov_b32 m0, s41
	ds_read_b128 v[184:187], v147 offset:16384
	ds_read_b128 v[202:205], v147 offset:17408
	ds_read_b128 v[206:209], v147 offset:18432
	ds_read_b128 v[210:213], v147 offset:19456
	ds_read_b128 v[214:217], v147 offset:20480
	ds_read_b128 v[218:221], v147 offset:21504
	ds_read_b128 v[222:225], v147 offset:22528
	ds_read_b128 v[226:229], v147 offset:23552
	global_load_lds_dwordx4 v[176:177], off
	s_add_i32 m0, s41, 0x2000
	s_add_u32 s44, s16, 0x80000
	v_lshl_add_u64 v[180:181], s[16:17], 0, v[130:131]
	s_addc_u32 s45, s17, 0
	s_add_i32 s41, s46, s0
	global_load_lds_dwordx4 v[180:181], off
	s_mov_b32 m0, s41
	v_lshl_add_u64 v[188:189], s[18:19], 0, v[132:133]
	global_load_lds_dwordx4 v0, s[44:45]
	v_lshl_add_u64 v[182:183], s[44:45], 0, v[130:131]
	s_add_i32 m0, s41, 0x2000
	s_nop 0
	global_load_lds_dwordx4 v[182:183], off
	v_lshl_add_u64 v[182:183], s[18:19], 0, v[134:135]
	s_mov_b32 m0, s1
	s_nop 0
	global_load_lds_dwordx4 v[182:183], off
	s_mov_b32 m0, s14
	s_nop 0
	global_load_lds_dwordx4 v[188:189], off
	s_waitcnt vmcnt(8)
	s_waitcnt lgkmcnt(0)
	s_barrier
; #define PG8_STAGE(bufoff, gbase, voff) do { _Pragma("unroll") for (int _i = 0; _i < 2; ++_i) \
;         __builtin_amdgcn_global_load_lds((const unsigned*)((const char*)(gbase) + (voff)[_i]), (PG8_LAS unsigned*)(lds + (bufoff) + ldsw + _i * 8192), 16, 0, 0); } while (0)
; #define PG8_LDA(dst, b, h) do { _Pragma("unroll") for (int m = 0; m < 4; ++m) _Pragma("unroll") for (int k = 0; k < 2; ++k) dst[m][k] = *(const PG8_LAS bf16x8*)(lds + PG8_SA(b, h) + aoff + m * 2048 + k * 1024); } while (0)
; #define PG8_LDB(dst, b, h) do { _Pragma("unroll") for (int n = 0; n < 2; ++n) _Pragma("unroll") for (int k = 0; k < 2; ++k) dst[n][k] = *(const PG8_LAS bf16x8*)(lds + PG8_SB(b, h) + boff + n * 2048 + k * 1024); } while (0)
; #define PG8_MMA(ai, bj, At, Bt) do { __builtin_amdgcn_s_setprio(1); _Pragma("unroll") for (int m = 0; m < 4; ++m) _Pragma("unroll") for (int n = 0; n < 2; ++n) _Pragma("unroll") for (int k = 0; k < 2; ++k) \
;         acc[ai][bj][m][n] = __builtin_amdgcn_mfma_f32_16x16x32_bf16(Bt[n][k], At[m][k], acc[ai][bj][m][n], 0, 0, 0); __builtin_amdgcn_s_setprio(0); } while (0)
; #define PG8_WAIT_V(n) asm volatile("s_waitcnt vmcnt(" #n ")" ::: "memory")
; #define PG8_WAIT_L(n) asm volatile("s_waitcnt lgkmcnt(" #n ")" ::: "memory")
; #define PG8_BAR __builtin_amdgcn_s_barrier()
; #define PG8_SCHED __builtin_amdgcn_sched_barrier(0)
; template <class Epi, class Sched, bool ALIGN_EPI = false, bool SP2 = false>
; __device__ __forceinline__ void gemm_phase(PG8_LAS unsigned char* lds, const Gemm g, const Sched& S, const Epi& E) {
;     ...
;             PG8_WAIT_V(8); PG8_WAIT_L(0); PG8_BAR; PG8_MMA(1, 0, At, B0); PG8_MMA(1, 1, At, B1); PG8_BAR; PG8_SCHED;
;             PG8_LDB(B0, 1, 0); PG8_LDB(B1, 1, 1); PG8_SCHED; PG8_LDA(At, 1, 0); PG8_STAGE(PG8_SA(0, 1), a2 + hstep, voffA);
;             PG8_WAIT_V(8); PG8_WAIT_L(0); PG8_BAR; PG8_MMA(0, 0, At, B0); PG8_MMA(0, 1, At, B1); PG8_BAR; PG8_SCHED;
;             PG8_LDA(At, 1, 1); PG8_STAGE(PG8_SB(1, 0), b3, voffB); PG8_STAGE(PG8_SB(1, 1), b3 + hstep, voffB); PG8_STAGE(PG8_SA(1, 0), a3, voffA);
	s_setprio 1
	s_waitcnt lgkmcnt(0)
	v_mfma_f32_16x16x32_bf16 v[62:65], v[140:143], v[184:187], v[62:65]
	v_mfma_f32_16x16x32_bf16 v[58:61], v[152:155], v[184:187], v[58:61]
	v_mfma_f32_16x16x32_bf16 v[54:57], v[140:143], v[206:209], v[54:57]
	v_mfma_f32_16x16x32_bf16 v[46:49], v[152:155], v[206:209], v[46:49]
	v_mfma_f32_16x16x32_bf16 v[38:41], v[140:143], v[214:217], v[38:41]
	v_mfma_f32_16x16x32_bf16 v[30:33], v[152:155], v[214:217], v[30:33]
	v_mfma_f32_16x16x32_bf16 v[22:25], v[140:143], v[222:225], v[22:25]
	v_mfma_f32_16x16x32_bf16 v[14:17], v[152:155], v[222:225], v[14:17]
	v_mfma_f32_16x16x32_bf16 v[62:65], v[148:151], v[202:205], v[62:65]
	v_mfma_f32_16x16x32_bf16 v[58:61], v[156:159], v[202:205], v[58:61]
	v_mfma_f32_16x16x32_bf16 v[54:57], v[148:151], v[210:213], v[54:57]
	v_mfma_f32_16x16x32_bf16 v[46:49], v[156:159], v[210:213], v[46:49]
	v_mfma_f32_16x16x32_bf16 v[38:41], v[148:151], v[218:221], v[38:41]
	v_mfma_f32_16x16x32_bf16 v[30:33], v[156:159], v[218:221], v[30:33]
	v_mfma_f32_16x16x32_bf16 v[22:25], v[148:151], v[226:229], v[22:25]
	v_mfma_f32_16x16x32_bf16 v[14:17], v[156:159], v[226:229], v[14:17]
	s_setprio 0
	s_setprio 1
	v_mfma_f32_16x16x32_bf16 v[50:53], v[160:163], v[184:187], v[50:53]
	v_mfma_f32_16x16x32_bf16 v[42:45], v[168:171], v[184:187], v[42:45]
	v_mfma_f32_16x16x32_bf16 v[34:37], v[160:163], v[206:209], v[34:37]
	v_mfma_f32_16x16x32_bf16 v[26:29], v[168:171], v[206:209], v[26:29]
	v_mfma_f32_16x16x32_bf16 v[18:21], v[160:163], v[214:217], v[18:21]
	v_mfma_f32_16x16x32_bf16 v[10:13], v[168:171], v[214:217], v[10:13]
	v_mfma_f32_16x16x32_bf16 v[6:9], v[160:163], v[222:225], v[6:9]
	v_mfma_f32_16x16x32_bf16 v[2:5], v[168:171], v[222:225], v[2:5]
	v_mfma_f32_16x16x32_bf16 v[50:53], v[164:167], v[202:205], v[50:53]
	v_mfma_f32_16x16x32_bf16 v[42:45], v[172:175], v[202:205], v[42:45]
	v_mfma_f32_16x16x32_bf16 v[34:37], v[164:167], v[210:213], v[34:37]
	v_mfma_f32_16x16x32_bf16 v[26:29], v[172:175], v[210:213], v[26:29]
	v_mfma_f32_16x16x32_bf16 v[18:21], v[164:167], v[218:221], v[18:21]
	v_mfma_f32_16x16x32_bf16 v[10:13], v[172:175], v[218:221], v[10:13]
	v_mfma_f32_16x16x32_bf16 v[6:9], v[164:167], v[226:229], v[6:9]
	v_mfma_f32_16x16x32_bf16 v[2:5], v[172:175], v[226:229], v[2:5]
	s_setprio 0
	s_barrier
	s_add_i32 s41, 0, 0x18000
	s_add_i32 s44, 0, 0x1c000
	v_add_u32_e32 v156, s41, v145
	v_add_u32_e32 v172, s44, v145
	ds_read_b128 v[140:143], v156
	ds_read_b128 v[148:151], v156 offset:1024
	ds_read_b128 v[152:155], v156 offset:2048
	ds_read_b128 v[156:159], v156 offset:3072
	ds_read_b128 v[160:163], v172
	ds_read_b128 v[164:167], v172 offset:1024
	ds_read_b128 v[168:171], v172 offset:2048
	ds_read_b128 v[172:175], v172 offset:3072
	s_add_u32 s18, s18, 0x80000
	s_addc_u32 s19, s19, 0
	s_mov_b32 m0, s22
	v_lshl_add_u64 v[230:231], s[18:19], 0, v[134:135]
	ds_read_b128 v[184:187], v147 offset:32768
	ds_read_b128 v[202:205], v147 offset:33792
	ds_read_b128 v[206:209], v147 offset:34816
	ds_read_b128 v[210:213], v147 offset:35840
	ds_read_b128 v[214:217], v147 offset:36864
	ds_read_b128 v[218:221], v147 offset:37888
	ds_read_b128 v[222:225], v147 offset:38912
	ds_read_b128 v[226:229], v147 offset:39936
	global_load_lds_dwordx4 v[230:231], off
	v_lshl_add_u64 v[230:231], s[18:19], 0, v[132:133]
	s_mov_b32 m0, s24
	s_nop 0
	global_load_lds_dwordx4 v[230:231], off
	s_waitcnt vmcnt(8)
	s_waitcnt lgkmcnt(0)
	s_barrier
	s_setprio 1
	s_waitcnt lgkmcnt(0)
	v_mfma_f32_16x16x32_bf16 v[126:129], v[140:143], v[184:187], v[126:129]
	v_mfma_f32_16x16x32_bf16 v[122:125], v[152:155], v[184:187], v[122:125]
	v_mfma_f32_16x16x32_bf16 v[118:121], v[140:143], v[206:209], v[118:121]
	v_mfma_f32_16x16x32_bf16 v[110:113], v[152:155], v[206:209], v[110:113]
	v_mfma_f32_16x16x32_bf16 v[102:105], v[140:143], v[214:217], v[102:105]
	v_mfma_f32_16x16x32_bf16 v[94:97], v[152:155], v[214:217], v[94:97]
	v_mfma_f32_16x16x32_bf16 v[86:89], v[140:143], v[222:225], v[86:89]
	v_mfma_f32_16x16x32_bf16 v[78:81], v[152:155], v[222:225], v[78:81]
	v_mfma_f32_16x16x32_bf16 v[126:129], v[148:151], v[202:205], v[126:129]
	v_mfma_f32_16x16x32_bf16 v[122:125], v[156:159], v[202:205], v[122:125]
	v_mfma_f32_16x16x32_bf16 v[118:121], v[148:151], v[210:213], v[118:121]
	v_mfma_f32_16x16x32_bf16 v[110:113], v[156:159], v[210:213], v[110:113]
	v_mfma_f32_16x16x32_bf16 v[102:105], v[148:151], v[218:221], v[102:105]
	v_mfma_f32_16x16x32_bf16 v[94:97], v[156:159], v[218:221], v[94:97]
	v_mfma_f32_16x16x32_bf16 v[86:89], v[148:151], v[226:229], v[86:89]
	v_mfma_f32_16x16x32_bf16 v[78:81], v[156:159], v[226:229], v[78:81]
	s_setprio 0
	s_setprio 1
	v_mfma_f32_16x16x32_bf16 v[114:117], v[160:163], v[184:187], v[114:117]
	v_mfma_f32_16x16x32_bf16 v[106:109], v[168:171], v[184:187], v[106:109]
	v_mfma_f32_16x16x32_bf16 v[98:101], v[160:163], v[206:209], v[98:101]
	v_mfma_f32_16x16x32_bf16 v[90:93], v[168:171], v[206:209], v[90:93]
	v_mfma_f32_16x16x32_bf16 v[82:85], v[160:163], v[214:217], v[82:85]
	v_mfma_f32_16x16x32_bf16 v[74:77], v[168:171], v[214:217], v[74:77]
	v_mfma_f32_16x16x32_bf16 v[70:73], v[160:163], v[222:225], v[70:73]
	v_mfma_f32_16x16x32_bf16 v[66:69], v[168:171], v[222:225], v[66:69]
	v_mfma_f32_16x16x32_bf16 v[114:117], v[164:167], v[202:205], v[114:117]
	v_mfma_f32_16x16x32_bf16 v[106:109], v[172:175], v[202:205], v[106:109]
	v_mfma_f32_16x16x32_bf16 v[98:101], v[164:167], v[210:213], v[98:101]
	v_mfma_f32_16x16x32_bf16 v[90:93], v[172:175], v[210:213], v[90:93]
	v_mfma_f32_16x16x32_bf16 v[82:85], v[164:167], v[218:221], v[82:85]
	v_mfma_f32_16x16x32_bf16 v[74:77], v[172:175], v[218:221], v[74:77]
	v_mfma_f32_16x16x32_bf16 v[70:73], v[164:167], v[226:229], v[70:73]
	v_mfma_f32_16x16x32_bf16 v[66:69], v[172:175], v[226:229], v[66:69]
	s_setprio 0
	s_barrier
; #define PG8_STAGE(bufoff, gbase, voff) do { _Pragma("unroll") for (int _i = 0; _i < 2; ++_i) \
;         __builtin_amdgcn_global_load_lds((const unsigned*)((const char*)(gbase) + (voff)[_i]), (PG8_LAS unsigned*)(lds + (bufoff) + ldsw + _i * 8192), 16, 0, 0); } while (0)
; #define PG8_LDA(dst, b, h) do { _Pragma("unroll") for (int m = 0; m < 4; ++m) _Pragma("unroll") for (int k = 0; k < 2; ++k) dst[m][k] = *(const PG8_LAS bf16x8*)(lds + PG8_SA(b, h) + aoff + m * 2048 + k * 1024); } while (0)
; #define PG8_MMA(ai, bj, At, Bt) do { __builtin_amdgcn_s_setprio(1); _Pragma("unroll") for (int m = 0; m < 4; ++m) _Pragma("unroll") for (int n = 0; n < 2; ++n) _Pragma("unroll") for (int k = 0; k < 2; ++k) \
;         acc[ai][bj][m][n] = __builtin_amdgcn_mfma_f32_16x16x32_bf16(Bt[n][k], At[m][k], acc[ai][bj][m][n], 0, 0, 0); __builtin_amdgcn_s_setprio(0); } while (0)
; #define PG8_WAIT_V(n) asm volatile("s_waitcnt vmcnt(" #n ")" ::: "memory")
; #define PG8_WAIT_L(n) asm volatile("s_waitcnt lgkmcnt(" #n ")" ::: "memory")
; #define PG8_BAR __builtin_amdgcn_s_barrier()
; #define PG8_SCHED __builtin_amdgcn_sched_barrier(0)
; template <class Epi, class Sched, bool ALIGN_EPI = false, bool SP2 = false>
; __device__ __forceinline__ void gemm_phase(PG8_LAS unsigned char* lds, const Gemm g, const Sched& S, const Epi& E) {
;     ...
;             PG8_WAIT_V(8); PG8_WAIT_L(0); PG8_BAR; PG8_MMA(0, 0, At, B0); PG8_MMA(0, 1, At, B1); PG8_BAR; PG8_SCHED;
;             PG8_LDA(At, 1, 1); PG8_STAGE(PG8_SB(1, 0), b3, voffB); PG8_STAGE(PG8_SB(1, 1), b3 + hstep, voffB); PG8_STAGE(PG8_SA(1, 0), a3, voffA);
;             PG8_WAIT_V(8); PG8_WAIT_L(0); PG8_BAR; PG8_MMA(1, 0, At, B0); PG8_MMA(1, 1, At, B1); PG8_BAR; PG8_SCHED;
	s_add_i32 s18, s41, s0
	v_lshl_add_u64 v[176:177], v[176:177], 0, s[36:37]
	s_mov_b32 m0, s18
	ds_read_b128 v[184:187], v147 offset:49152
	ds_read_b128 v[202:205], v147 offset:50176
	ds_read_b128 v[206:209], v147 offset:51200
	ds_read_b128 v[210:213], v147 offset:52224
	ds_read_b128 v[214:217], v147 offset:53248
	ds_read_b128 v[218:221], v147 offset:54272
	ds_read_b128 v[222:225], v147 offset:55296
	ds_read_b128 v[226:229], v147 offset:56320
	global_load_lds_dwordx4 v[176:177], off
	s_add_i32 m0, s18, 0x2000
	s_add_u32 s16, s16, 0x80080
	v_lshl_add_u64 v[176:177], v[180:181], 0, s[36:37]
	s_addc_u32 s17, s17, 0
	s_add_i32 s18, s44, s0
	global_load_lds_dwordx4 v[176:177], off
	s_mov_b32 m0, s18
	s_nop 0
	global_load_lds_dwordx4 v0, s[16:17]
	v_lshl_add_u64 v[176:177], s[16:17], 0, v[130:131]
	s_add_i32 m0, s18, 0x2000
	s_nop 0
	global_load_lds_dwordx4 v[176:177], off
	v_lshl_add_u64 v[176:177], v[182:183], 0, s[36:37]
	s_mov_b32 m0, s25
	s_nop 0
	global_load_lds_dwordx4 v[176:177], off
	v_lshl_add_u64 v[176:177], v[188:189], 0, s[36:37]
	s_mov_b32 m0, s28
	s_nop 0
	global_load_lds_dwordx4 v[176:177], off
	s_waitcnt vmcnt(8)
	s_waitcnt lgkmcnt(0)
	s_barrier
	s_setprio 1
	s_waitcnt lgkmcnt(0)
	v_mfma_f32_16x16x32_bf16 v[62:65], v[140:143], v[184:187], v[62:65]
	v_mfma_f32_16x16x32_bf16 v[58:61], v[152:155], v[184:187], v[58:61]
	v_mfma_f32_16x16x32_bf16 v[54:57], v[140:143], v[206:209], v[54:57]
	v_mfma_f32_16x16x32_bf16 v[46:49], v[152:155], v[206:209], v[46:49]
	v_mfma_f32_16x16x32_bf16 v[38:41], v[140:143], v[214:217], v[38:41]
	v_mfma_f32_16x16x32_bf16 v[30:33], v[152:155], v[214:217], v[30:33]
	v_mfma_f32_16x16x32_bf16 v[22:25], v[140:143], v[222:225], v[22:25]
	v_mfma_f32_16x16x32_bf16 v[14:17], v[152:155], v[222:225], v[14:17]
	v_mfma_f32_16x16x32_bf16 v[62:65], v[148:151], v[202:205], v[62:65]
	v_mfma_f32_16x16x32_bf16 v[58:61], v[156:159], v[202:205], v[58:61]
	v_mfma_f32_16x16x32_bf16 v[54:57], v[148:151], v[210:213], v[54:57]
	v_mfma_f32_16x16x32_bf16 v[46:49], v[156:159], v[210:213], v[46:49]
	v_mfma_f32_16x16x32_bf16 v[38:41], v[148:151], v[218:221], v[38:41]
	v_mfma_f32_16x16x32_bf16 v[30:33], v[156:159], v[218:221], v[30:33]
	v_mfma_f32_16x16x32_bf16 v[22:25], v[148:151], v[226:229], v[22:25]
	v_mfma_f32_16x16x32_bf16 v[14:17], v[156:159], v[226:229], v[14:17]
	s_setprio 0
	s_setprio 1
	v_mfma_f32_16x16x32_bf16 v[50:53], v[160:163], v[184:187], v[50:53]
	v_mfma_f32_16x16x32_bf16 v[42:45], v[168:171], v[184:187], v[42:45]
	v_mfma_f32_16x16x32_bf16 v[34:37], v[160:163], v[206:209], v[34:37]
	v_mfma_f32_16x16x32_bf16 v[26:29], v[168:171], v[206:209], v[26:29]
	v_mfma_f32_16x16x32_bf16 v[18:21], v[160:163], v[214:217], v[18:21]
	v_mfma_f32_16x16x32_bf16 v[10:13], v[168:171], v[214:217], v[10:13]
	v_mfma_f32_16x16x32_bf16 v[6:9], v[160:163], v[222:225], v[6:9]
	v_mfma_f32_16x16x32_bf16 v[2:5], v[168:171], v[222:225], v[2:5]
	v_mfma_f32_16x16x32_bf16 v[50:53], v[164:167], v[202:205], v[50:53]
	v_mfma_f32_16x16x32_bf16 v[42:45], v[172:175], v[202:205], v[42:45]
	v_mfma_f32_16x16x32_bf16 v[34:37], v[164:167], v[210:213], v[34:37]
	v_mfma_f32_16x16x32_bf16 v[26:29], v[172:175], v[210:213], v[26:29]
	v_mfma_f32_16x16x32_bf16 v[18:21], v[164:167], v[218:221], v[18:21]
	v_mfma_f32_16x16x32_bf16 v[10:13], v[172:175], v[218:221], v[10:13]
	v_mfma_f32_16x16x32_bf16 v[6:9], v[164:167], v[226:229], v[6:9]
	v_mfma_f32_16x16x32_bf16 v[2:5], v[172:175], v[226:229], v[2:5]
	s_setprio 0
	s_barrier
	s_add_i32 s40, s40, 2
	s_add_u32 s20, s20, 0x100
	s_addc_u32 s21, s21, 0
	s_add_u32 s38, s38, 0x100
	s_addc_u32 s39, s39, 0
	s_cmp_gt_u32 s40, 29
	s_cbranch_scc0 .LBB0_496
	s_and_b64 vcc, exec, s[4:5]
	s_cbranch_vccz .LBB0_499
	s_barrier
